# GEMM main loops (ph0 / ph4 / ph5): the per-cluster s_setprio flips deleted (A/B of lever 7.4b); on top of v076
# baseline (speedup 1.0000x reference)
.LBB0_192:
	s_add_u32 s20, s18, 0xfffc0080
	s_addc_u32 s21, s19, -1
	s_add_i32 s50, 0, 0x10000
	s_cmp_eq_u32 s49, 12
	s_cselect_b32 s23, s11, s21
	s_cselect_b32 s22, s45, s20
	v_add_u32_e32 v138, s50, v140
	s_cselect_b32 s21, s9, s48
	s_cselect_b32 s20, s46, s47
	s_add_i32 s52, 0, 0x14000
	ds_read_b128 v[144:147], v138
	ds_read_b128 v[148:151], v138 offset:1024
	ds_read_b128 v[160:163], v138 offset:2048
	ds_read_b128 v[164:167], v138 offset:3072
	v_add_u32_e32 v138, s52, v140
	ds_read_b128 v[168:171], v138
	ds_read_b128 v[172:175], v138 offset:1024
	ds_read_b128 v[176:179], v138 offset:2048
	ds_read_b128 v[180:183], v138 offset:3072
	v_lshl_add_u64 v[138:139], s[18:19], 0, v[134:135]
	s_add_i32 m0, s17, 0xc000
	ds_read_b128 v[184:187], v142
	ds_read_b128 v[188:191], v142 offset:1024
	ds_read_b128 v[192:195], v142 offset:2048
	ds_read_b128 v[196:199], v142 offset:3072
	ds_read_b128 v[200:203], v142 offset:4096
	ds_read_b128 v[204:207], v142 offset:5120
	ds_read_b128 v[228:231], v142 offset:6144
	ds_read_b128 v[232:235], v142 offset:7168
	global_load_lds_dwordx4 v[138:139], off
	v_lshl_add_u64 v[138:139], s[18:19], 0, v[136:137]
	s_add_i32 m0, s17, 0xe000
	s_nop 0
	global_load_lds_dwordx4 v[138:139], off
	s_waitcnt vmcnt(8)
	s_waitcnt lgkmcnt(0)
	s_barrier
	s_waitcnt lgkmcnt(0)
	v_mfma_f32_16x16x32_bf16 v[126:129], v[144:147], v[184:187], v[126:129]
	v_mfma_f32_16x16x32_bf16 v[122:125], v[160:163], v[184:187], v[122:125]
	v_mfma_f32_16x16x32_bf16 v[110:113], v[144:147], v[192:195], v[110:113]
	v_mfma_f32_16x16x32_bf16 v[106:109], v[160:163], v[192:195], v[106:109]
	v_mfma_f32_16x16x32_bf16 v[98:101], v[144:147], v[200:203], v[98:101]
	v_mfma_f32_16x16x32_bf16 v[90:93], v[160:163], v[200:203], v[90:93]
	v_mfma_f32_16x16x32_bf16 v[82:85], v[144:147], v[228:231], v[82:85]
	v_mfma_f32_16x16x32_bf16 v[74:77], v[160:163], v[228:231], v[74:77]
	v_mfma_f32_16x16x32_bf16 v[126:129], v[148:151], v[188:191], v[126:129]
	v_mfma_f32_16x16x32_bf16 v[122:125], v[164:167], v[188:191], v[122:125]
	v_mfma_f32_16x16x32_bf16 v[110:113], v[148:151], v[196:199], v[110:113]
	v_mfma_f32_16x16x32_bf16 v[106:109], v[164:167], v[196:199], v[106:109]
	v_mfma_f32_16x16x32_bf16 v[98:101], v[148:151], v[204:207], v[98:101]
	v_mfma_f32_16x16x32_bf16 v[90:93], v[164:167], v[204:207], v[90:93]
	v_mfma_f32_16x16x32_bf16 v[82:85], v[148:151], v[232:235], v[82:85]
	v_mfma_f32_16x16x32_bf16 v[74:77], v[164:167], v[232:235], v[74:77]
	v_mfma_f32_16x16x32_bf16 v[118:121], v[168:171], v[184:187], v[118:121]
	v_mfma_f32_16x16x32_bf16 v[114:117], v[176:179], v[184:187], v[114:117]
	v_mfma_f32_16x16x32_bf16 v[102:105], v[168:171], v[192:195], v[102:105]
	v_mfma_f32_16x16x32_bf16 v[94:97], v[176:179], v[192:195], v[94:97]
	v_mfma_f32_16x16x32_bf16 v[86:89], v[168:171], v[200:203], v[86:89]
	v_mfma_f32_16x16x32_bf16 v[78:81], v[176:179], v[200:203], v[78:81]
	v_mfma_f32_16x16x32_bf16 v[70:73], v[168:171], v[228:231], v[70:73]
	v_mfma_f32_16x16x32_bf16 v[66:69], v[176:179], v[228:231], v[66:69]
	v_mfma_f32_16x16x32_bf16 v[118:121], v[172:175], v[188:191], v[118:121]
	v_mfma_f32_16x16x32_bf16 v[114:117], v[180:183], v[188:191], v[114:117]
	v_mfma_f32_16x16x32_bf16 v[102:105], v[172:175], v[196:199], v[102:105]
	v_mfma_f32_16x16x32_bf16 v[94:97], v[180:183], v[196:199], v[94:97]
	v_mfma_f32_16x16x32_bf16 v[86:89], v[172:175], v[204:207], v[86:89]
	v_mfma_f32_16x16x32_bf16 v[78:81], v[180:183], v[204:207], v[78:81]
	v_mfma_f32_16x16x32_bf16 v[70:73], v[172:175], v[232:235], v[70:73]
	v_mfma_f32_16x16x32_bf16 v[66:69], v[180:183], v[232:235], v[66:69]
	s_barrier
	s_add_i32 s50, s50, s36
	v_lshl_add_u64 v[138:139], s[20:21], 0, v[130:131]
	s_mov_b32 m0, s50
	ds_read_b128 v[184:187], v142 offset:16384
	ds_read_b128 v[188:191], v142 offset:17408
	ds_read_b128 v[192:195], v142 offset:18432
	ds_read_b128 v[196:199], v142 offset:19456
	ds_read_b128 v[200:203], v142 offset:20480
	ds_read_b128 v[204:207], v142 offset:21504
	ds_read_b128 v[228:231], v142 offset:22528
	ds_read_b128 v[232:235], v142 offset:23552
	global_load_lds_dwordx4 v[138:139], off
	s_add_i32 m0, s50, 0x2000
	s_add_u32 s50, s20, 0x40000
	v_lshl_add_u64 v[152:153], s[20:21], 0, v[132:133]
	s_addc_u32 s51, s21, 0
	s_add_i32 s52, s52, s36
	global_load_lds_dwordx4 v[152:153], off
	v_lshl_add_u64 v[236:237], s[50:51], 0, v[130:131]
	s_mov_b32 m0, s52
	v_lshl_add_u64 v[238:239], s[22:23], 0, v[132:133]
	global_load_lds_dwordx4 v[236:237], off
	v_lshl_add_u64 v[236:237], s[50:51], 0, v[132:133]
	s_add_i32 m0, s52, 0x2000
	s_nop 0
	global_load_lds_dwordx4 v[236:237], off
	v_lshl_add_u64 v[236:237], s[22:23], 0, v[130:131]
	s_mov_b32 m0, s17
	s_nop 0
	global_load_lds_dwordx4 v[236:237], off
	s_mov_b32 m0, s37
	s_nop 0
	global_load_lds_dwordx4 v[238:239], off
	s_waitcnt vmcnt(8)
	s_waitcnt lgkmcnt(0)
	s_barrier
	s_waitcnt lgkmcnt(0)
	v_mfma_f32_16x16x32_bf16 v[62:65], v[144:147], v[184:187], v[62:65]
	v_mfma_f32_16x16x32_bf16 v[58:61], v[160:163], v[184:187], v[58:61]
	v_mfma_f32_16x16x32_bf16 v[50:53], v[144:147], v[192:195], v[50:53]
	v_mfma_f32_16x16x32_bf16 v[42:45], v[160:163], v[192:195], v[42:45]
	v_mfma_f32_16x16x32_bf16 v[34:37], v[144:147], v[200:203], v[34:37]
	v_mfma_f32_16x16x32_bf16 v[26:29], v[160:163], v[200:203], v[26:29]
	v_mfma_f32_16x16x32_bf16 v[18:21], v[144:147], v[228:231], v[18:21]
	v_mfma_f32_16x16x32_bf16 v[10:13], v[160:163], v[228:231], v[10:13]
	v_mfma_f32_16x16x32_bf16 v[62:65], v[148:151], v[188:191], v[62:65]
	v_mfma_f32_16x16x32_bf16 v[58:61], v[164:167], v[188:191], v[58:61]
	v_mfma_f32_16x16x32_bf16 v[50:53], v[148:151], v[196:199], v[50:53]
	v_mfma_f32_16x16x32_bf16 v[42:45], v[164:167], v[196:199], v[42:45]
	v_mfma_f32_16x16x32_bf16 v[34:37], v[148:151], v[204:207], v[34:37]
	v_mfma_f32_16x16x32_bf16 v[26:29], v[164:167], v[204:207], v[26:29]
	v_mfma_f32_16x16x32_bf16 v[18:21], v[148:151], v[232:235], v[18:21]
	v_mfma_f32_16x16x32_bf16 v[10:13], v[164:167], v[232:235], v[10:13]
	v_mfma_f32_16x16x32_bf16 v[54:57], v[168:171], v[184:187], v[54:57]
	v_mfma_f32_16x16x32_bf16 v[46:49], v[176:179], v[184:187], v[46:49]
	v_mfma_f32_16x16x32_bf16 v[38:41], v[168:171], v[192:195], v[38:41]
	v_mfma_f32_16x16x32_bf16 v[30:33], v[176:179], v[192:195], v[30:33]
	v_mfma_f32_16x16x32_bf16 v[22:25], v[168:171], v[200:203], v[22:25]
	v_mfma_f32_16x16x32_bf16 v[14:17], v[176:179], v[200:203], v[14:17]
	v_mfma_f32_16x16x32_bf16 v[6:9], v[168:171], v[228:231], v[6:9]
	v_mfma_f32_16x16x32_bf16 v[2:5], v[176:179], v[228:231], v[2:5]
	v_mfma_f32_16x16x32_bf16 v[54:57], v[172:175], v[188:191], v[54:57]
	v_mfma_f32_16x16x32_bf16 v[46:49], v[180:183], v[188:191], v[46:49]
	v_mfma_f32_16x16x32_bf16 v[38:41], v[172:175], v[196:199], v[38:41]
	v_mfma_f32_16x16x32_bf16 v[30:33], v[180:183], v[196:199], v[30:33]
	v_mfma_f32_16x16x32_bf16 v[22:25], v[172:175], v[204:207], v[22:25]
	v_mfma_f32_16x16x32_bf16 v[14:17], v[180:183], v[204:207], v[14:17]
	v_mfma_f32_16x16x32_bf16 v[6:9], v[172:175], v[232:235], v[6:9]
	v_mfma_f32_16x16x32_bf16 v[2:5], v[180:183], v[232:235], v[2:5]
	s_barrier
	s_add_i32 s50, 0, 0x18000
	v_add_u32_e32 v143, s50, v140
	s_add_i32 s51, 0, 0x1c000
	ds_read_b128 v[144:147], v143
	ds_read_b128 v[148:151], v143 offset:1024
	ds_read_b128 v[160:163], v143 offset:2048
	ds_read_b128 v[164:167], v143 offset:3072
	v_add_u32_e32 v143, s51, v140
	ds_read_b128 v[168:171], v143
	ds_read_b128 v[172:175], v143 offset:1024
	ds_read_b128 v[176:179], v143 offset:2048
	ds_read_b128 v[180:183], v143 offset:3072
	s_add_u32 s22, s22, 0x40000
	s_addc_u32 s23, s23, 0
	s_mov_b32 m0, s38
	v_lshl_add_u64 v[240:241], s[22:23], 0, v[130:131]
	ds_read_b128 v[184:187], v142 offset:32768
	ds_read_b128 v[188:191], v142 offset:33792
	ds_read_b128 v[192:195], v142 offset:34816
	ds_read_b128 v[196:199], v142 offset:35840
	ds_read_b128 v[200:203], v142 offset:36864
	ds_read_b128 v[204:207], v142 offset:37888
	ds_read_b128 v[228:231], v142 offset:38912
	ds_read_b128 v[232:235], v142 offset:39936
	global_load_lds_dwordx4 v[240:241], off
	v_lshl_add_u64 v[240:241], s[22:23], 0, v[132:133]
	s_mov_b32 m0, s39
	s_nop 0
	global_load_lds_dwordx4 v[240:241], off
	s_waitcnt vmcnt(8)
	s_waitcnt lgkmcnt(0)
	s_barrier
	s_waitcnt lgkmcnt(0)
	v_mfma_f32_16x16x32_bf16 v[126:129], v[144:147], v[184:187], v[126:129]
	v_mfma_f32_16x16x32_bf16 v[122:125], v[160:163], v[184:187], v[122:125]
	v_mfma_f32_16x16x32_bf16 v[110:113], v[144:147], v[192:195], v[110:113]
	v_mfma_f32_16x16x32_bf16 v[106:109], v[160:163], v[192:195], v[106:109]
	v_mfma_f32_16x16x32_bf16 v[98:101], v[144:147], v[200:203], v[98:101]
	v_mfma_f32_16x16x32_bf16 v[90:93], v[160:163], v[200:203], v[90:93]
	v_mfma_f32_16x16x32_bf16 v[82:85], v[144:147], v[228:231], v[82:85]
	v_mfma_f32_16x16x32_bf16 v[74:77], v[160:163], v[228:231], v[74:77]
	v_mfma_f32_16x16x32_bf16 v[126:129], v[148:151], v[188:191], v[126:129]
	v_mfma_f32_16x16x32_bf16 v[122:125], v[164:167], v[188:191], v[122:125]
	v_mfma_f32_16x16x32_bf16 v[110:113], v[148:151], v[196:199], v[110:113]
	v_mfma_f32_16x16x32_bf16 v[106:109], v[164:167], v[196:199], v[106:109]
	v_mfma_f32_16x16x32_bf16 v[98:101], v[148:151], v[204:207], v[98:101]
	v_mfma_f32_16x16x32_bf16 v[90:93], v[164:167], v[204:207], v[90:93]
	v_mfma_f32_16x16x32_bf16 v[82:85], v[148:151], v[232:235], v[82:85]
	v_mfma_f32_16x16x32_bf16 v[74:77], v[164:167], v[232:235], v[74:77]
	v_mfma_f32_16x16x32_bf16 v[118:121], v[168:171], v[184:187], v[118:121]
	v_mfma_f32_16x16x32_bf16 v[114:117], v[176:179], v[184:187], v[114:117]
	v_mfma_f32_16x16x32_bf16 v[102:105], v[168:171], v[192:195], v[102:105]
	v_mfma_f32_16x16x32_bf16 v[94:97], v[176:179], v[192:195], v[94:97]
	v_mfma_f32_16x16x32_bf16 v[86:89], v[168:171], v[200:203], v[86:89]
	v_mfma_f32_16x16x32_bf16 v[78:81], v[176:179], v[200:203], v[78:81]
	v_mfma_f32_16x16x32_bf16 v[70:73], v[168:171], v[228:231], v[70:73]
	v_mfma_f32_16x16x32_bf16 v[66:69], v[176:179], v[228:231], v[66:69]
	v_mfma_f32_16x16x32_bf16 v[118:121], v[172:175], v[188:191], v[118:121]
	v_mfma_f32_16x16x32_bf16 v[114:117], v[180:183], v[188:191], v[114:117]
	v_mfma_f32_16x16x32_bf16 v[102:105], v[172:175], v[196:199], v[102:105]
	v_mfma_f32_16x16x32_bf16 v[94:97], v[180:183], v[196:199], v[94:97]
	v_mfma_f32_16x16x32_bf16 v[86:89], v[172:175], v[204:207], v[86:89]
	v_mfma_f32_16x16x32_bf16 v[78:81], v[180:183], v[204:207], v[78:81]
	v_mfma_f32_16x16x32_bf16 v[70:73], v[172:175], v[232:235], v[70:73]
	v_mfma_f32_16x16x32_bf16 v[66:69], v[180:183], v[232:235], v[66:69]
	s_barrier
	s_add_i32 s22, s50, s36
	v_lshl_add_u64 v[138:139], v[138:139], 0, s[76:77]
	s_mov_b32 m0, s22
	ds_read_b128 v[184:187], v142 offset:49152
	ds_read_b128 v[188:191], v142 offset:50176
	ds_read_b128 v[192:195], v142 offset:51200
	ds_read_b128 v[196:199], v142 offset:52224
	ds_read_b128 v[200:203], v142 offset:53248
	ds_read_b128 v[204:207], v142 offset:54272
	ds_read_b128 v[228:231], v142 offset:55296
	ds_read_b128 v[232:235], v142 offset:56320
	global_load_lds_dwordx4 v[138:139], off
	s_add_i32 m0, s22, 0x2000
	s_add_u32 s20, s20, 0x40080
	v_lshl_add_u64 v[138:139], v[152:153], 0, s[76:77]
	s_addc_u32 s21, s21, 0
	s_add_i32 s22, s51, s36
	global_load_lds_dwordx4 v[138:139], off
	v_lshl_add_u64 v[138:139], s[20:21], 0, v[130:131]
	s_mov_b32 m0, s22
	s_nop 0
	global_load_lds_dwordx4 v[138:139], off
	v_lshl_add_u64 v[138:139], s[20:21], 0, v[132:133]
	s_add_i32 m0, s22, 0x2000
	s_nop 0
	global_load_lds_dwordx4 v[138:139], off
	v_lshl_add_u64 v[138:139], v[236:237], 0, s[76:77]
	s_mov_b32 m0, s40
	s_nop 0
	global_load_lds_dwordx4 v[138:139], off
	v_lshl_add_u64 v[138:139], v[238:239], 0, s[76:77]
	s_mov_b32 m0, s41
	s_nop 0
	global_load_lds_dwordx4 v[138:139], off
	s_waitcnt vmcnt(8)
	s_waitcnt lgkmcnt(0)
	s_barrier
	s_waitcnt lgkmcnt(0)
	v_mfma_f32_16x16x32_bf16 v[62:65], v[144:147], v[184:187], v[62:65]
	v_mfma_f32_16x16x32_bf16 v[58:61], v[160:163], v[184:187], v[58:61]
	v_mfma_f32_16x16x32_bf16 v[50:53], v[144:147], v[192:195], v[50:53]
	v_mfma_f32_16x16x32_bf16 v[42:45], v[160:163], v[192:195], v[42:45]
	v_mfma_f32_16x16x32_bf16 v[34:37], v[144:147], v[200:203], v[34:37]
	v_mfma_f32_16x16x32_bf16 v[26:29], v[160:163], v[200:203], v[26:29]
	v_mfma_f32_16x16x32_bf16 v[18:21], v[144:147], v[228:231], v[18:21]
	v_mfma_f32_16x16x32_bf16 v[10:13], v[160:163], v[228:231], v[10:13]
	v_mfma_f32_16x16x32_bf16 v[62:65], v[148:151], v[188:191], v[62:65]
	v_mfma_f32_16x16x32_bf16 v[58:61], v[164:167], v[188:191], v[58:61]
	v_mfma_f32_16x16x32_bf16 v[50:53], v[148:151], v[196:199], v[50:53]
	v_mfma_f32_16x16x32_bf16 v[42:45], v[164:167], v[196:199], v[42:45]
	v_mfma_f32_16x16x32_bf16 v[34:37], v[148:151], v[204:207], v[34:37]
	v_mfma_f32_16x16x32_bf16 v[26:29], v[164:167], v[204:207], v[26:29]
	v_mfma_f32_16x16x32_bf16 v[18:21], v[148:151], v[232:235], v[18:21]
	v_mfma_f32_16x16x32_bf16 v[10:13], v[164:167], v[232:235], v[10:13]
	v_mfma_f32_16x16x32_bf16 v[54:57], v[168:171], v[184:187], v[54:57]
	v_mfma_f32_16x16x32_bf16 v[46:49], v[176:179], v[184:187], v[46:49]
	v_mfma_f32_16x16x32_bf16 v[38:41], v[168:171], v[192:195], v[38:41]
	v_mfma_f32_16x16x32_bf16 v[30:33], v[176:179], v[192:195], v[30:33]
	v_mfma_f32_16x16x32_bf16 v[22:25], v[168:171], v[200:203], v[22:25]
	v_mfma_f32_16x16x32_bf16 v[14:17], v[176:179], v[200:203], v[14:17]
	v_mfma_f32_16x16x32_bf16 v[6:9], v[168:171], v[228:231], v[6:9]
	v_mfma_f32_16x16x32_bf16 v[2:5], v[176:179], v[228:231], v[2:5]
	v_mfma_f32_16x16x32_bf16 v[54:57], v[172:175], v[188:191], v[54:57]
	v_mfma_f32_16x16x32_bf16 v[46:49], v[180:183], v[188:191], v[46:49]
	v_mfma_f32_16x16x32_bf16 v[38:41], v[172:175], v[196:199], v[38:41]
	v_mfma_f32_16x16x32_bf16 v[30:33], v[180:183], v[196:199], v[30:33]
	v_mfma_f32_16x16x32_bf16 v[22:25], v[172:175], v[204:207], v[22:25]
	v_mfma_f32_16x16x32_bf16 v[14:17], v[180:183], v[204:207], v[14:17]
	v_mfma_f32_16x16x32_bf16 v[6:9], v[172:175], v[232:235], v[6:9]
	v_mfma_f32_16x16x32_bf16 v[2:5], v[180:183], v[232:235], v[2:5]
	s_barrier
	s_add_i32 s49, s49, 2
	s_add_u32 s18, s18, 0x100
	s_addc_u32 s19, s19, 0
	s_add_u32 s47, s47, 0x100
	s_addc_u32 s48, s48, 0
	s_cmp_gt_u32 s49, 13
	s_cbranch_scc0 .LBB0_192
	v_lshl_add_u32 v144, s16, 8, v1
	v_lshl_or_b32 v143, s44, 8, v141
	v_ashrrev_i32_e32 v145, 31, v144
	v_lshlrev_b64 v[138:139], 7, v[144:145]
	v_add_u32_e32 v145, 12, v143
	v_cndmask_b32_e64 v145, v145, v143, s[0:1]
	v_cvt_pk_bf16_f32 v126, v126, v127
	v_cvt_pk_bf16_f32 v127, v128, v129
	v_cvt_pk_bf16_f32 v128, v122, v123
	v_ashrrev_i32_e32 v122, 6, v145
	v_ashrrev_i32_e32 v123, 31, v122
	v_lshlrev_b64 v[122:123], 21, v[122:123]
	v_lshl_add_u64 v[122:123], s[6:7], 0, v[122:123]
	v_and_b32_e32 v145, 60, v145
	v_cvt_pk_bf16_f32 v129, v124, v125
	v_lshl_add_u64 v[124:125], v[122:123], 0, v[138:139]
	v_lshlrev_b32_e32 v154, 1, v145
	v_permlane16_swap_b32_e32 v126, v128
	v_permlane16_swap_b32_e32 v127, v129
	v_lshl_add_u64 v[124:125], v[124:125], 0, v[154:155]
	global_store_dwordx4 v[124:125], v[126:129], off
	v_or_b32_e32 v124, 0x80, v143
	v_add_u32_e32 v125, 0x8c, v143
	v_cndmask_b32_e64 v126, v125, v124, s[0:1]
	v_cvt_pk_bf16_f32 v118, v118, v119
	v_cvt_pk_bf16_f32 v119, v120, v121
	v_cvt_pk_bf16_f32 v120, v114, v115
	v_ashrrev_i32_e32 v114, 6, v126
	v_ashrrev_i32_e32 v115, 31, v114
	v_lshlrev_b64 v[114:115], 21, v[114:115]
	v_cvt_pk_bf16_f32 v121, v116, v117
	v_lshl_add_u64 v[114:115], s[6:7], 0, v[114:115]
	v_and_b32_e32 v116, 60, v126
	v_lshl_add_u64 v[124:125], v[114:115], 0, v[138:139]
	v_lshlrev_b32_e32 v116, 1, v116
	v_mov_b32_e32 v117, v155
	v_permlane16_swap_b32_e32 v118, v120
	v_permlane16_swap_b32_e32 v119, v121
	v_lshl_add_u64 v[124:125], v[124:125], 0, v[116:117]
	global_store_dwordx4 v[124:125], v[118:121], off
	v_cvt_pk_bf16_f32 v110, v110, v111
	v_cvt_pk_bf16_f32 v111, v112, v113
	v_cvt_pk_bf16_f32 v112, v106, v107
	v_cvt_pk_bf16_f32 v113, v108, v109
	v_cvt_pk_bf16_f32 v102, v102, v103
	s_nop 1
	v_or_b32_e32 v118, 16, v144
	v_ashrrev_i32_e32 v119, 31, v118
	v_lshlrev_b64 v[118:119], 7, v[118:119]
	v_lshl_add_u64 v[106:107], v[122:123], 0, v[118:119]
	v_cvt_pk_bf16_f32 v103, v104, v105
	v_cvt_pk_bf16_f32 v104, v94, v95
	v_cvt_pk_bf16_f32 v105, v96, v97
	v_lshl_add_u64 v[94:95], v[114:115], 0, v[118:119]
	v_permlane16_swap_b32_e32 v110, v112
	v_permlane16_swap_b32_e32 v111, v113
	v_lshl_add_u64 v[106:107], v[106:107], 0, v[154:155]
	v_permlane16_swap_b32_e32 v102, v104
	v_permlane16_swap_b32_e32 v103, v105
	v_lshl_add_u64 v[94:95], v[94:95], 0, v[116:117]
	global_store_dwordx4 v[106:107], v[110:113], off
	global_store_dwordx4 v[94:95], v[102:105], off
	v_or_b32_e32 v94, 32, v144
	v_ashrrev_i32_e32 v95, 31, v94
	v_lshlrev_b64 v[102:103], 7, v[94:95]
	v_cvt_pk_bf16_f32 v94, v98, v99
	v_cvt_pk_bf16_f32 v95, v100, v101
	v_cvt_pk_bf16_f32 v96, v90, v91
	v_cvt_pk_bf16_f32 v97, v92, v93
	v_lshl_add_u64 v[90:91], v[122:123], 0, v[102:103]
	v_cvt_pk_bf16_f32 v86, v86, v87
	v_cvt_pk_bf16_f32 v87, v88, v89
	v_cvt_pk_bf16_f32 v88, v78, v79
	v_cvt_pk_bf16_f32 v89, v80, v81
	v_lshl_add_u64 v[78:79], v[114:115], 0, v[102:103]
	v_permlane16_swap_b32_e32 v94, v96
	v_permlane16_swap_b32_e32 v95, v97
	v_lshl_add_u64 v[90:91], v[90:91], 0, v[154:155]
	v_permlane16_swap_b32_e32 v86, v88
	v_permlane16_swap_b32_e32 v87, v89
	v_lshl_add_u64 v[78:79], v[78:79], 0, v[116:117]
	global_store_dwordx4 v[90:91], v[94:97], off
	global_store_dwordx4 v[78:79], v[86:89], off
	v_or_b32_e32 v78, 48, v144
	v_ashrrev_i32_e32 v79, 31, v78
	v_lshlrev_b64 v[86:87], 7, v[78:79]
	v_cvt_pk_bf16_f32 v78, v82, v83
	v_cvt_pk_bf16_f32 v79, v84, v85
	v_cvt_pk_bf16_f32 v80, v74, v75
	v_cvt_pk_bf16_f32 v81, v76, v77
	v_lshl_add_u64 v[74:75], v[122:123], 0, v[86:87]
	v_cvt_pk_bf16_f32 v70, v70, v71
	v_cvt_pk_bf16_f32 v71, v72, v73
	v_cvt_pk_bf16_f32 v72, v66, v67
	v_cvt_pk_bf16_f32 v73, v68, v69
	v_lshl_add_u64 v[66:67], v[114:115], 0, v[86:87]
	v_permlane16_swap_b32_e32 v78, v80
	v_permlane16_swap_b32_e32 v79, v81
	v_lshl_add_u64 v[74:75], v[74:75], 0, v[154:155]
	v_permlane16_swap_b32_e32 v70, v72
	v_permlane16_swap_b32_e32 v71, v73
	v_lshl_add_u64 v[66:67], v[66:67], 0, v[116:117]
	s_mov_b64 s[18:19], 0x4000
	global_store_dwordx4 v[74:75], v[78:81], off
	global_store_dwordx4 v[66:67], v[70:73], off
	v_lshl_add_u64 v[66:67], v[138:139], 0, s[18:19]
	v_cvt_pk_bf16_f32 v62, v62, v63
	v_cvt_pk_bf16_f32 v63, v64, v65
	v_cvt_pk_bf16_f32 v64, v58, v59
	v_cvt_pk_bf16_f32 v65, v60, v61
	v_lshl_add_u64 v[58:59], v[122:123], 0, v[66:67]
	v_cvt_pk_bf16_f32 v54, v54, v55
	v_cvt_pk_bf16_f32 v55, v56, v57
	v_cvt_pk_bf16_f32 v56, v46, v47
	v_cvt_pk_bf16_f32 v57, v48, v49
	v_lshl_add_u64 v[46:47], v[114:115], 0, v[66:67]
	v_permlane16_swap_b32_e32 v62, v64
	v_permlane16_swap_b32_e32 v63, v65
	v_lshl_add_u64 v[58:59], v[58:59], 0, v[154:155]
	v_permlane16_swap_b32_e32 v54, v56
	v_permlane16_swap_b32_e32 v55, v57
	v_lshl_add_u64 v[46:47], v[46:47], 0, v[116:117]
	s_mov_b64 s[18:19], 0x4800
	global_store_dwordx4 v[58:59], v[62:65], off
	global_store_dwordx4 v[46:47], v[54:57], off
	v_cvt_pk_bf16_f32 v46, v50, v51
	v_cvt_pk_bf16_f32 v47, v52, v53
	v_cvt_pk_bf16_f32 v48, v42, v43
	v_cvt_pk_bf16_f32 v49, v44, v45
	v_cvt_pk_bf16_f32 v38, v38, v39
	s_nop 1
	v_lshl_add_u64 v[54:55], v[138:139], 0, s[18:19]
	v_lshl_add_u64 v[42:43], v[122:123], 0, v[54:55]
	v_cvt_pk_bf16_f32 v39, v40, v41
	v_cvt_pk_bf16_f32 v40, v30, v31
	v_cvt_pk_bf16_f32 v41, v32, v33
	v_lshl_add_u64 v[30:31], v[114:115], 0, v[54:55]
	v_permlane16_swap_b32_e32 v46, v48
	v_permlane16_swap_b32_e32 v47, v49
	v_lshl_add_u64 v[42:43], v[42:43], 0, v[154:155]
	v_permlane16_swap_b32_e32 v38, v40
	v_permlane16_swap_b32_e32 v39, v41
	v_lshl_add_u64 v[30:31], v[30:31], 0, v[116:117]
	s_mov_b64 s[18:19], 0x5000
	global_store_dwordx4 v[42:43], v[46:49], off
	global_store_dwordx4 v[30:31], v[38:41], off
	v_cvt_pk_bf16_f32 v30, v34, v35
	v_cvt_pk_bf16_f32 v31, v36, v37
	v_cvt_pk_bf16_f32 v32, v26, v27
	v_cvt_pk_bf16_f32 v33, v28, v29
	v_cvt_pk_bf16_f32 v22, v22, v23
	s_nop 1
	v_lshl_add_u64 v[38:39], v[138:139], 0, s[18:19]
	v_lshl_add_u64 v[26:27], v[122:123], 0, v[38:39]
	v_cvt_pk_bf16_f32 v23, v24, v25
	v_cvt_pk_bf16_f32 v24, v14, v15
	v_cvt_pk_bf16_f32 v25, v16, v17
	v_lshl_add_u64 v[14:15], v[114:115], 0, v[38:39]
	v_permlane16_swap_b32_e32 v30, v32
	v_permlane16_swap_b32_e32 v31, v33
	v_lshl_add_u64 v[26:27], v[26:27], 0, v[154:155]
	v_permlane16_swap_b32_e32 v22, v24
	v_permlane16_swap_b32_e32 v23, v25
	v_lshl_add_u64 v[14:15], v[14:15], 0, v[116:117]
	s_mov_b64 s[18:19], 0x5800
	global_store_dwordx4 v[26:27], v[30:33], off
	global_store_dwordx4 v[14:15], v[22:25], off
	v_cvt_pk_bf16_f32 v14, v18, v19
	v_cvt_pk_bf16_f32 v15, v20, v21
	v_cvt_pk_bf16_f32 v16, v10, v11
	v_cvt_pk_bf16_f32 v17, v12, v13
	v_cvt_pk_bf16_f32 v6, v6, v7
	s_nop 1
	v_lshl_add_u64 v[22:23], v[138:139], 0, s[18:19]
	v_lshl_add_u64 v[10:11], v[122:123], 0, v[22:23]
	v_cvt_pk_bf16_f32 v7, v8, v9
	v_cvt_pk_bf16_f32 v8, v2, v3
	v_cvt_pk_bf16_f32 v9, v4, v5
	v_lshl_add_u64 v[2:3], v[114:115], 0, v[22:23]
	v_permlane16_swap_b32_e32 v14, v16
	v_permlane16_swap_b32_e32 v15, v17
	v_lshl_add_u64 v[10:11], v[10:11], 0, v[154:155]
	v_permlane16_swap_b32_e32 v6, v8
	v_permlane16_swap_b32_e32 v7, v9
	v_lshl_add_u64 v[2:3], v[2:3], 0, v[116:117]
	s_and_b64 vcc, exec, s[2:3]
	s_mov_b32 s44, s8
	s_mov_b32 s16, s10
	s_mov_b64 s[20:21], s[14:15]
	s_mov_b64 s[18:19], s[12:13]
	global_store_dwordx4 v[10:11], v[14:17], off
	global_store_dwordx4 v[2:3], v[6:9], off
	s_cbranch_vccz .LBB0_185
	s_waitcnt vmcnt(0)
	s_cmpk_gt_u32 s29, 0xff
	s_cbranch_scc1 .LBB0_196
	s_barrier

.LBB0_225:
	s_add_u32 s34, s20, s30
	s_addc_u32 s35, s21, s31
	s_add_u32 s34, s34, 0x100
	s_addc_u32 s35, s35, 0
	s_add_u32 s70, s65, s30
	s_addc_u32 s71, s66, s31
	s_add_i32 s72, 0, 0x10000
	s_cmpk_eq_i32 s30, 0x700
	s_cselect_b32 s37, s25, s35
	s_cselect_b32 s36, s67, s34
	s_cselect_b32 s35, s23, s71
	s_cselect_b32 s34, s68, s70
	s_add_i32 s73, 0, 0x14000
	v_add_u32_e32 v160, s72, v108
	v_add_u32_e32 v176, s73, v108
	ds_read_b128 v[110:113], v160
	ds_read_b128 v[146:149], v160 offset:1024
	ds_read_b128 v[150:153], v160 offset:2048
	ds_read_b128 v[160:163], v160 offset:3072
	ds_read_b128 v[164:167], v176
	ds_read_b128 v[168:171], v176 offset:1024
	ds_read_b128 v[172:175], v176 offset:2048
	ds_read_b128 v[176:179], v176 offset:3072
	v_lshl_add_u64 v[232:233], v[96:97], 0, s[30:31]
	s_add_i32 m0, s55, 0xc000
	ds_read_b128 v[180:183], v109
	ds_read_b128 v[184:187], v109 offset:1024
	ds_read_b128 v[188:191], v109 offset:2048
	ds_read_b128 v[192:195], v109 offset:3072
	ds_read_b128 v[196:199], v109 offset:4096
	ds_read_b128 v[200:203], v109 offset:5120
	ds_read_b128 v[204:207], v109 offset:6144
	ds_read_b128 v[228:231], v109 offset:7168
	global_load_lds_dwordx4 v[232:233], off
	v_lshl_add_u64 v[232:233], v[106:107], 0, s[30:31]
	s_add_i32 m0, s55, 0xe000
	s_nop 0
	global_load_lds_dwordx4 v[232:233], off
	s_waitcnt vmcnt(8)
	s_waitcnt lgkmcnt(0)
	s_barrier
	s_waitcnt lgkmcnt(0)
	v_mfma_f32_16x16x32_bf16 v[142:145], v[110:113], v[180:183], v[142:145]
	v_mfma_f32_16x16x32_bf16 v[138:141], v[150:153], v[180:183], v[138:141]
	v_mfma_f32_16x16x32_bf16 v[126:129], v[110:113], v[188:191], v[126:129]
	v_mfma_f32_16x16x32_bf16 v[122:125], v[150:153], v[188:191], v[122:125]
	v_mfma_f32_16x16x32_bf16 v[102:105], v[110:113], v[196:199], v[102:105]
	v_mfma_f32_16x16x32_bf16 v[98:101], v[150:153], v[196:199], v[98:101]
	v_mfma_f32_16x16x32_bf16 v[78:81], v[110:113], v[204:207], v[78:81]
	v_mfma_f32_16x16x32_bf16 v[74:77], v[150:153], v[204:207], v[74:77]
	v_mfma_f32_16x16x32_bf16 v[142:145], v[146:149], v[184:187], v[142:145]
	v_mfma_f32_16x16x32_bf16 v[138:141], v[160:163], v[184:187], v[138:141]
	v_mfma_f32_16x16x32_bf16 v[126:129], v[146:149], v[192:195], v[126:129]
	v_mfma_f32_16x16x32_bf16 v[122:125], v[160:163], v[192:195], v[122:125]
	v_mfma_f32_16x16x32_bf16 v[102:105], v[146:149], v[200:203], v[102:105]
	v_mfma_f32_16x16x32_bf16 v[98:101], v[160:163], v[200:203], v[98:101]
	v_mfma_f32_16x16x32_bf16 v[78:81], v[146:149], v[228:231], v[78:81]
	v_mfma_f32_16x16x32_bf16 v[74:77], v[160:163], v[228:231], v[74:77]
	v_mfma_f32_16x16x32_bf16 v[134:137], v[164:167], v[180:183], v[134:137]
	v_mfma_f32_16x16x32_bf16 v[130:133], v[172:175], v[180:183], v[130:133]
	v_mfma_f32_16x16x32_bf16 v[118:121], v[164:167], v[188:191], v[118:121]
	v_mfma_f32_16x16x32_bf16 v[114:117], v[172:175], v[188:191], v[114:117]
	v_mfma_f32_16x16x32_bf16 v[86:89], v[164:167], v[196:199], v[86:89]
	v_mfma_f32_16x16x32_bf16 v[82:85], v[172:175], v[196:199], v[82:85]
	v_mfma_f32_16x16x32_bf16 v[70:73], v[164:167], v[204:207], v[70:73]
	v_mfma_f32_16x16x32_bf16 v[66:69], v[172:175], v[204:207], v[66:69]
	v_mfma_f32_16x16x32_bf16 v[134:137], v[168:171], v[184:187], v[134:137]
	v_mfma_f32_16x16x32_bf16 v[130:133], v[176:179], v[184:187], v[130:133]
	v_mfma_f32_16x16x32_bf16 v[118:121], v[168:171], v[192:195], v[118:121]
	v_mfma_f32_16x16x32_bf16 v[114:117], v[176:179], v[192:195], v[114:117]
	v_mfma_f32_16x16x32_bf16 v[86:89], v[168:171], v[200:203], v[86:89]
	v_mfma_f32_16x16x32_bf16 v[82:85], v[176:179], v[200:203], v[82:85]
	v_mfma_f32_16x16x32_bf16 v[70:73], v[168:171], v[228:231], v[70:73]
	v_mfma_f32_16x16x32_bf16 v[66:69], v[176:179], v[228:231], v[66:69]
	s_barrier
	s_add_i32 s70, s72, s50
	v_lshl_add_u64 v[232:233], s[34:35], 0, v[154:155]
	s_mov_b32 m0, s70
	ds_read_b128 v[180:183], v109 offset:16384
	ds_read_b128 v[184:187], v109 offset:17408
	ds_read_b128 v[188:191], v109 offset:18432
	ds_read_b128 v[192:195], v109 offset:19456
	ds_read_b128 v[196:199], v109 offset:20480
	ds_read_b128 v[200:203], v109 offset:21504
	ds_read_b128 v[204:207], v109 offset:22528
	ds_read_b128 v[228:231], v109 offset:23552
	global_load_lds_dwordx4 v[232:233], off
	s_add_i32 m0, s70, 0x2000
	s_add_u32 s70, s34, 0x40000
	v_lshl_add_u64 v[234:235], s[34:35], 0, v[90:91]
	s_addc_u32 s71, s35, 0
	s_add_i32 s72, s73, s50
	global_load_lds_dwordx4 v[234:235], off
	v_lshl_add_u64 v[236:237], s[70:71], 0, v[154:155]
	s_mov_b32 m0, s72
	v_lshl_add_u64 v[238:239], s[36:37], 0, v[90:91]
	global_load_lds_dwordx4 v[236:237], off
	v_lshl_add_u64 v[236:237], s[70:71], 0, v[90:91]
	s_add_i32 m0, s72, 0x2000
	s_nop 0
	global_load_lds_dwordx4 v[236:237], off
	v_lshl_add_u64 v[236:237], s[36:37], 0, v[154:155]
	s_mov_b32 m0, s55
	s_nop 0
	global_load_lds_dwordx4 v[236:237], off
	s_mov_b32 m0, s56
	s_nop 0
	global_load_lds_dwordx4 v[238:239], off
	s_waitcnt vmcnt(8)
	s_waitcnt lgkmcnt(0)
	s_barrier
	s_waitcnt lgkmcnt(0)
	v_mfma_f32_16x16x32_bf16 v[62:65], v[110:113], v[180:183], v[62:65]
	v_mfma_f32_16x16x32_bf16 v[58:61], v[150:153], v[180:183], v[58:61]
	v_mfma_f32_16x16x32_bf16 v[46:49], v[110:113], v[188:191], v[46:49]
	v_mfma_f32_16x16x32_bf16 v[42:45], v[150:153], v[188:191], v[42:45]
	v_mfma_f32_16x16x32_bf16 v[30:33], v[110:113], v[196:199], v[30:33]
	v_mfma_f32_16x16x32_bf16 v[26:29], v[150:153], v[196:199], v[26:29]
	v_mfma_f32_16x16x32_bf16 v[14:17], v[110:113], v[204:207], v[14:17]
	v_mfma_f32_16x16x32_bf16 v[10:13], v[150:153], v[204:207], v[10:13]
	v_mfma_f32_16x16x32_bf16 v[62:65], v[146:149], v[184:187], v[62:65]
	v_mfma_f32_16x16x32_bf16 v[58:61], v[160:163], v[184:187], v[58:61]
	v_mfma_f32_16x16x32_bf16 v[46:49], v[146:149], v[192:195], v[46:49]
	v_mfma_f32_16x16x32_bf16 v[42:45], v[160:163], v[192:195], v[42:45]
	v_mfma_f32_16x16x32_bf16 v[30:33], v[146:149], v[200:203], v[30:33]
	v_mfma_f32_16x16x32_bf16 v[26:29], v[160:163], v[200:203], v[26:29]
	v_mfma_f32_16x16x32_bf16 v[14:17], v[146:149], v[228:231], v[14:17]
	v_mfma_f32_16x16x32_bf16 v[10:13], v[160:163], v[228:231], v[10:13]
	v_mfma_f32_16x16x32_bf16 v[54:57], v[164:167], v[180:183], v[54:57]
	v_mfma_f32_16x16x32_bf16 v[50:53], v[172:175], v[180:183], v[50:53]
	v_mfma_f32_16x16x32_bf16 v[38:41], v[164:167], v[188:191], v[38:41]
	v_mfma_f32_16x16x32_bf16 v[34:37], v[172:175], v[188:191], v[34:37]
	v_mfma_f32_16x16x32_bf16 v[22:25], v[164:167], v[196:199], v[22:25]
	v_mfma_f32_16x16x32_bf16 v[18:21], v[172:175], v[196:199], v[18:21]
	v_mfma_f32_16x16x32_bf16 v[6:9], v[164:167], v[204:207], v[6:9]
	v_mfma_f32_16x16x32_bf16 v[2:5], v[172:175], v[204:207], v[2:5]
	v_mfma_f32_16x16x32_bf16 v[54:57], v[168:171], v[184:187], v[54:57]
	v_mfma_f32_16x16x32_bf16 v[50:53], v[176:179], v[184:187], v[50:53]
	v_mfma_f32_16x16x32_bf16 v[38:41], v[168:171], v[192:195], v[38:41]
	v_mfma_f32_16x16x32_bf16 v[34:37], v[176:179], v[192:195], v[34:37]
	v_mfma_f32_16x16x32_bf16 v[22:25], v[168:171], v[200:203], v[22:25]
	v_mfma_f32_16x16x32_bf16 v[18:21], v[176:179], v[200:203], v[18:21]
	v_mfma_f32_16x16x32_bf16 v[6:9], v[168:171], v[228:231], v[6:9]
	v_mfma_f32_16x16x32_bf16 v[2:5], v[176:179], v[228:231], v[2:5]
	s_barrier
	s_add_i32 s70, 0, 0x18000
	s_add_i32 s71, 0, 0x1c000
	v_add_u32_e32 v160, s70, v108
	v_add_u32_e32 v176, s71, v108
	ds_read_b128 v[110:113], v160
	ds_read_b128 v[146:149], v160 offset:1024
	ds_read_b128 v[150:153], v160 offset:2048
	ds_read_b128 v[160:163], v160 offset:3072
	ds_read_b128 v[164:167], v176
	ds_read_b128 v[168:171], v176 offset:1024
	ds_read_b128 v[172:175], v176 offset:2048
	ds_read_b128 v[176:179], v176 offset:3072
	s_add_u32 s36, s36, 0x40000
	s_addc_u32 s37, s37, 0
	s_mov_b32 m0, s57
	v_lshl_add_u64 v[240:241], s[36:37], 0, v[154:155]
	ds_read_b128 v[180:183], v109 offset:32768
	ds_read_b128 v[184:187], v109 offset:33792
	ds_read_b128 v[188:191], v109 offset:34816
	ds_read_b128 v[192:195], v109 offset:35840
	ds_read_b128 v[196:199], v109 offset:36864
	ds_read_b128 v[200:203], v109 offset:37888
	ds_read_b128 v[204:207], v109 offset:38912
	ds_read_b128 v[228:231], v109 offset:39936
	global_load_lds_dwordx4 v[240:241], off
	v_lshl_add_u64 v[240:241], s[36:37], 0, v[90:91]
	s_mov_b32 m0, s59
	s_nop 0
	global_load_lds_dwordx4 v[240:241], off
	s_waitcnt vmcnt(8)
	s_waitcnt lgkmcnt(0)
	s_barrier
	s_waitcnt lgkmcnt(0)
	v_mfma_f32_16x16x32_bf16 v[142:145], v[110:113], v[180:183], v[142:145]
	v_mfma_f32_16x16x32_bf16 v[138:141], v[150:153], v[180:183], v[138:141]
	v_mfma_f32_16x16x32_bf16 v[126:129], v[110:113], v[188:191], v[126:129]
	v_mfma_f32_16x16x32_bf16 v[122:125], v[150:153], v[188:191], v[122:125]
	v_mfma_f32_16x16x32_bf16 v[102:105], v[110:113], v[196:199], v[102:105]
	v_mfma_f32_16x16x32_bf16 v[98:101], v[150:153], v[196:199], v[98:101]
	v_mfma_f32_16x16x32_bf16 v[78:81], v[110:113], v[204:207], v[78:81]
	v_mfma_f32_16x16x32_bf16 v[74:77], v[150:153], v[204:207], v[74:77]
	v_mfma_f32_16x16x32_bf16 v[142:145], v[146:149], v[184:187], v[142:145]
	v_mfma_f32_16x16x32_bf16 v[138:141], v[160:163], v[184:187], v[138:141]
	v_mfma_f32_16x16x32_bf16 v[126:129], v[146:149], v[192:195], v[126:129]
	v_mfma_f32_16x16x32_bf16 v[122:125], v[160:163], v[192:195], v[122:125]
	v_mfma_f32_16x16x32_bf16 v[102:105], v[146:149], v[200:203], v[102:105]
	v_mfma_f32_16x16x32_bf16 v[98:101], v[160:163], v[200:203], v[98:101]
	v_mfma_f32_16x16x32_bf16 v[78:81], v[146:149], v[228:231], v[78:81]
	v_mfma_f32_16x16x32_bf16 v[74:77], v[160:163], v[228:231], v[74:77]
	v_mfma_f32_16x16x32_bf16 v[134:137], v[164:167], v[180:183], v[134:137]
	v_mfma_f32_16x16x32_bf16 v[130:133], v[172:175], v[180:183], v[130:133]
	v_mfma_f32_16x16x32_bf16 v[118:121], v[164:167], v[188:191], v[118:121]
	v_mfma_f32_16x16x32_bf16 v[114:117], v[172:175], v[188:191], v[114:117]
	v_mfma_f32_16x16x32_bf16 v[86:89], v[164:167], v[196:199], v[86:89]
	v_mfma_f32_16x16x32_bf16 v[82:85], v[172:175], v[196:199], v[82:85]
	v_mfma_f32_16x16x32_bf16 v[70:73], v[164:167], v[204:207], v[70:73]
	v_mfma_f32_16x16x32_bf16 v[66:69], v[172:175], v[204:207], v[66:69]
	v_mfma_f32_16x16x32_bf16 v[134:137], v[168:171], v[184:187], v[134:137]
	v_mfma_f32_16x16x32_bf16 v[130:133], v[176:179], v[184:187], v[130:133]
	v_mfma_f32_16x16x32_bf16 v[118:121], v[168:171], v[192:195], v[118:121]
	v_mfma_f32_16x16x32_bf16 v[114:117], v[176:179], v[192:195], v[114:117]
	v_mfma_f32_16x16x32_bf16 v[86:89], v[168:171], v[200:203], v[86:89]
	v_mfma_f32_16x16x32_bf16 v[82:85], v[176:179], v[200:203], v[82:85]
	v_mfma_f32_16x16x32_bf16 v[70:73], v[168:171], v[228:231], v[70:73]
	v_mfma_f32_16x16x32_bf16 v[66:69], v[176:179], v[228:231], v[66:69]
	s_barrier
	s_add_i32 s36, s70, s50
	v_lshl_add_u64 v[232:233], v[232:233], 0, s[76:77]
	s_mov_b32 m0, s36
	ds_read_b128 v[180:183], v109 offset:49152
	ds_read_b128 v[184:187], v109 offset:50176
	ds_read_b128 v[188:191], v109 offset:51200
	ds_read_b128 v[192:195], v109 offset:52224
	ds_read_b128 v[196:199], v109 offset:53248
	ds_read_b128 v[200:203], v109 offset:54272
	ds_read_b128 v[204:207], v109 offset:55296
	ds_read_b128 v[228:231], v109 offset:56320
	global_load_lds_dwordx4 v[232:233], off
	s_add_i32 m0, s36, 0x2000
	s_add_u32 s34, s34, 0x40080
	v_lshl_add_u64 v[232:233], v[234:235], 0, s[76:77]
	s_addc_u32 s35, s35, 0
	s_add_i32 s36, s71, s50
	global_load_lds_dwordx4 v[232:233], off
	v_lshl_add_u64 v[232:233], s[34:35], 0, v[154:155]
	s_mov_b32 m0, s36
	s_nop 0
	global_load_lds_dwordx4 v[232:233], off
	v_lshl_add_u64 v[232:233], s[34:35], 0, v[90:91]
	s_add_i32 m0, s36, 0x2000
	s_nop 0
	global_load_lds_dwordx4 v[232:233], off
	v_lshl_add_u64 v[232:233], v[236:237], 0, s[76:77]
	s_mov_b32 m0, s60
	s_nop 0
	global_load_lds_dwordx4 v[232:233], off
	v_lshl_add_u64 v[232:233], v[238:239], 0, s[76:77]
	s_mov_b32 m0, s62
	s_nop 0
	global_load_lds_dwordx4 v[232:233], off
	s_waitcnt vmcnt(8)
	s_waitcnt lgkmcnt(0)
	s_barrier
	s_waitcnt lgkmcnt(0)
	v_mfma_f32_16x16x32_bf16 v[62:65], v[110:113], v[180:183], v[62:65]
	v_mfma_f32_16x16x32_bf16 v[58:61], v[150:153], v[180:183], v[58:61]
	v_mfma_f32_16x16x32_bf16 v[46:49], v[110:113], v[188:191], v[46:49]
	v_mfma_f32_16x16x32_bf16 v[42:45], v[150:153], v[188:191], v[42:45]
	v_mfma_f32_16x16x32_bf16 v[30:33], v[110:113], v[196:199], v[30:33]
	v_mfma_f32_16x16x32_bf16 v[26:29], v[150:153], v[196:199], v[26:29]
	v_mfma_f32_16x16x32_bf16 v[14:17], v[110:113], v[204:207], v[14:17]
	v_mfma_f32_16x16x32_bf16 v[10:13], v[150:153], v[204:207], v[10:13]
	v_mfma_f32_16x16x32_bf16 v[62:65], v[146:149], v[184:187], v[62:65]
	v_mfma_f32_16x16x32_bf16 v[58:61], v[160:163], v[184:187], v[58:61]
	v_mfma_f32_16x16x32_bf16 v[46:49], v[146:149], v[192:195], v[46:49]
	v_mfma_f32_16x16x32_bf16 v[42:45], v[160:163], v[192:195], v[42:45]
	v_mfma_f32_16x16x32_bf16 v[30:33], v[146:149], v[200:203], v[30:33]
	v_mfma_f32_16x16x32_bf16 v[26:29], v[160:163], v[200:203], v[26:29]
	v_mfma_f32_16x16x32_bf16 v[14:17], v[146:149], v[228:231], v[14:17]
	v_mfma_f32_16x16x32_bf16 v[10:13], v[160:163], v[228:231], v[10:13]
	v_mfma_f32_16x16x32_bf16 v[54:57], v[164:167], v[180:183], v[54:57]
	v_mfma_f32_16x16x32_bf16 v[50:53], v[172:175], v[180:183], v[50:53]
	v_mfma_f32_16x16x32_bf16 v[38:41], v[164:167], v[188:191], v[38:41]
	v_mfma_f32_16x16x32_bf16 v[34:37], v[172:175], v[188:191], v[34:37]
	v_mfma_f32_16x16x32_bf16 v[22:25], v[164:167], v[196:199], v[22:25]
	v_mfma_f32_16x16x32_bf16 v[18:21], v[172:175], v[196:199], v[18:21]
	v_mfma_f32_16x16x32_bf16 v[6:9], v[164:167], v[204:207], v[6:9]
	v_mfma_f32_16x16x32_bf16 v[2:5], v[172:175], v[204:207], v[2:5]
	v_mfma_f32_16x16x32_bf16 v[54:57], v[168:171], v[184:187], v[54:57]
	v_mfma_f32_16x16x32_bf16 v[50:53], v[176:179], v[184:187], v[50:53]
	v_mfma_f32_16x16x32_bf16 v[38:41], v[168:171], v[192:195], v[38:41]
	v_mfma_f32_16x16x32_bf16 v[34:37], v[176:179], v[192:195], v[34:37]
	v_mfma_f32_16x16x32_bf16 v[22:25], v[168:171], v[200:203], v[22:25]
	v_mfma_f32_16x16x32_bf16 v[18:21], v[176:179], v[200:203], v[18:21]
	v_mfma_f32_16x16x32_bf16 v[6:9], v[168:171], v[228:231], v[6:9]
	v_mfma_f32_16x16x32_bf16 v[2:5], v[176:179], v[228:231], v[2:5]
	s_barrier
	s_add_i32 s69, s69, 2
	s_add_u32 s30, s30, 0x100
	s_addc_u32 s31, s31, 0
	s_cmp_gt_u32 s69, 13
	s_cbranch_scc0 .LBB0_225
	s_add_u32 s30, s65, 0xffffff00
	s_addc_u32 s31, s66, -1
	s_andn2_b64 vcc, exec, s[2:3]
	s_cbranch_vccnz .LBB0_228
	v_mov_b32_e32 v2, 0
	s_mov_b32 s14, s22
	s_mov_b32 s10, s24
	s_mov_b64 s[20:21], s[28:29]
	s_mov_b32 s63, s64
	v_mov_b32_e32 v3, v2
	v_mov_b32_e32 v4, v2
	v_mov_b32_e32 v5, v2
	v_mov_b32_e32 v6, v2
	v_mov_b32_e32 v7, v2
	v_mov_b32_e32 v8, v2
	v_mov_b32_e32 v9, v2
	v_mov_b32_e32 v18, v2
	v_mov_b32_e32 v19, v2
	v_mov_b32_e32 v20, v2
	v_mov_b32_e32 v21, v2
	v_mov_b32_e32 v22, v2
	v_mov_b32_e32 v23, v2
	v_mov_b32_e32 v24, v2
	v_mov_b32_e32 v25, v2
	v_mov_b32_e32 v34, v2
	v_mov_b32_e32 v35, v2
	v_mov_b32_e32 v36, v2
	v_mov_b32_e32 v37, v2
	v_mov_b32_e32 v38, v2
	v_mov_b32_e32 v39, v2
	v_mov_b32_e32 v40, v2
	v_mov_b32_e32 v41, v2
	v_mov_b32_e32 v50, v2
	v_mov_b32_e32 v51, v2
	v_mov_b32_e32 v52, v2
	v_mov_b32_e32 v53, v2
	v_mov_b32_e32 v54, v2
	v_mov_b32_e32 v55, v2
	v_mov_b32_e32 v56, v2
	v_mov_b32_e32 v57, v2
	v_mov_b32_e32 v10, v2
	v_mov_b32_e32 v11, v2
	v_mov_b32_e32 v12, v2
	v_mov_b32_e32 v13, v2
	v_mov_b32_e32 v14, v2
	v_mov_b32_e32 v15, v2
	v_mov_b32_e32 v16, v2
	v_mov_b32_e32 v17, v2
	v_mov_b32_e32 v26, v2
	v_mov_b32_e32 v27, v2
	v_mov_b32_e32 v28, v2
	v_mov_b32_e32 v29, v2
	v_mov_b32_e32 v30, v2
	v_mov_b32_e32 v31, v2
	v_mov_b32_e32 v32, v2
	v_mov_b32_e32 v33, v2
	v_mov_b32_e32 v42, v2
	v_mov_b32_e32 v43, v2
	v_mov_b32_e32 v44, v2
	v_mov_b32_e32 v45, v2
	v_mov_b32_e32 v46, v2
	v_mov_b32_e32 v47, v2
	v_mov_b32_e32 v48, v2
	v_mov_b32_e32 v49, v2
	v_mov_b32_e32 v58, v2
	v_mov_b32_e32 v59, v2
	v_mov_b32_e32 v60, v2
	v_mov_b32_e32 v61, v2
	v_mov_b32_e32 v62, v2
	v_mov_b32_e32 v63, v2
	v_mov_b32_e32 v64, v2
	v_mov_b32_e32 v65, v2
	v_mov_b32_e32 v66, v2
	v_mov_b32_e32 v67, v2
	v_mov_b32_e32 v68, v2
	v_mov_b32_e32 v69, v2
	v_mov_b32_e32 v70, v2
	v_mov_b32_e32 v71, v2
	v_mov_b32_e32 v72, v2
	v_mov_b32_e32 v73, v2
	v_mov_b32_e32 v82, v2
	v_mov_b32_e32 v83, v2
	v_mov_b32_e32 v84, v2
	v_mov_b32_e32 v85, v2
	v_mov_b32_e32 v86, v2
	v_mov_b32_e32 v87, v2
	v_mov_b32_e32 v88, v2
	v_mov_b32_e32 v89, v2
	v_mov_b32_e32 v114, v2
	v_mov_b32_e32 v115, v2
	v_mov_b32_e32 v116, v2
	v_mov_b32_e32 v117, v2
	v_mov_b32_e32 v118, v2
	v_mov_b32_e32 v119, v2
	v_mov_b32_e32 v120, v2
	v_mov_b32_e32 v121, v2
	v_mov_b32_e32 v130, v2
	v_mov_b32_e32 v131, v2
	v_mov_b32_e32 v132, v2
	v_mov_b32_e32 v133, v2
	v_mov_b32_e32 v134, v2
	v_mov_b32_e32 v135, v2
	v_mov_b32_e32 v136, v2
	v_mov_b32_e32 v137, v2
	v_mov_b32_e32 v74, v2
	v_mov_b32_e32 v75, v2
	v_mov_b32_e32 v76, v2
	v_mov_b32_e32 v77, v2
	v_mov_b32_e32 v78, v2
	v_mov_b32_e32 v79, v2
	v_mov_b32_e32 v80, v2
	v_mov_b32_e32 v81, v2
	v_mov_b32_e32 v98, v2
	v_mov_b32_e32 v99, v2
	v_mov_b32_e32 v100, v2
	v_mov_b32_e32 v101, v2
	v_mov_b32_e32 v102, v2
	v_mov_b32_e32 v103, v2
	v_mov_b32_e32 v104, v2
	v_mov_b32_e32 v105, v2
	v_mov_b32_e32 v122, v2
	v_mov_b32_e32 v123, v2
	v_mov_b32_e32 v124, v2
	v_mov_b32_e32 v125, v2
	v_mov_b32_e32 v126, v2
	v_mov_b32_e32 v127, v2
	v_mov_b32_e32 v128, v2
	v_mov_b32_e32 v129, v2
	v_mov_b32_e32 v138, v2
	v_mov_b32_e32 v139, v2
	v_mov_b32_e32 v140, v2
	v_mov_b32_e32 v141, v2
	v_mov_b32_e32 v142, v2
	v_mov_b32_e32 v143, v2
	v_mov_b32_e32 v144, v2
	v_mov_b32_e32 v145, v2
	s_andn2_b64 vcc, exec, s[0:1]
	s_cbranch_vccnz .LBB0_229
	s_branch .LBB0_230

.LBB0_584:
	s_add_u32 s12, s10, 0xfffc0080
	s_addc_u32 s13, s11, -1
	s_add_i32 s41, 0, 0x10000
	s_cmp_eq_u32 s40, 12
	s_cselect_b32 s37, s1, s13
	s_cselect_b32 s36, s9, s12
	v_add_u32_e32 v142, s41, v144
	s_cselect_b32 s13, s27, s39
	s_cselect_b32 s12, s29, s38
	s_add_i32 s60, 0, 0x14000
	ds_read_b128 v[138:141], v142
	ds_read_b128 v[148:151], v142 offset:1024
	ds_read_b128 v[160:163], v142 offset:2048
	ds_read_b128 v[164:167], v142 offset:3072
	v_add_u32_e32 v142, s60, v144
	ds_read_b128 v[168:171], v142
	ds_read_b128 v[172:175], v142 offset:1024
	ds_read_b128 v[176:179], v142 offset:2048
	ds_read_b128 v[180:183], v142 offset:3072
	v_lshl_add_u64 v[142:143], s[10:11], 0, v[134:135]
	s_add_i32 m0, s49, 0xc000
	ds_read_b128 v[184:187], v146
	ds_read_b128 v[188:191], v146 offset:1024
	ds_read_b128 v[192:195], v146 offset:2048
	ds_read_b128 v[196:199], v146 offset:3072
	ds_read_b128 v[200:203], v146 offset:4096
	ds_read_b128 v[204:207], v146 offset:5120
	ds_read_b128 v[228:231], v146 offset:6144
	ds_read_b128 v[232:235], v146 offset:7168
	global_load_lds_dwordx4 v[142:143], off
	v_lshl_add_u64 v[142:143], s[10:11], 0, v[136:137]
	s_add_i32 m0, s49, 0xe000
	s_nop 0
	global_load_lds_dwordx4 v[142:143], off
	s_waitcnt vmcnt(8)
	s_waitcnt lgkmcnt(0)
	s_barrier
	s_waitcnt lgkmcnt(0)
	v_mfma_f32_16x16x32_bf16 v[126:129], v[138:141], v[184:187], v[126:129]
	v_mfma_f32_16x16x32_bf16 v[122:125], v[160:163], v[184:187], v[122:125]
	v_mfma_f32_16x16x32_bf16 v[110:113], v[138:141], v[192:195], v[110:113]
	v_mfma_f32_16x16x32_bf16 v[106:109], v[160:163], v[192:195], v[106:109]
	v_mfma_f32_16x16x32_bf16 v[94:97], v[138:141], v[200:203], v[94:97]
	v_mfma_f32_16x16x32_bf16 v[90:93], v[160:163], v[200:203], v[90:93]
	v_mfma_f32_16x16x32_bf16 v[78:81], v[138:141], v[228:231], v[78:81]
	v_mfma_f32_16x16x32_bf16 v[74:77], v[160:163], v[228:231], v[74:77]
	v_mfma_f32_16x16x32_bf16 v[126:129], v[148:151], v[188:191], v[126:129]
	v_mfma_f32_16x16x32_bf16 v[122:125], v[164:167], v[188:191], v[122:125]
	v_mfma_f32_16x16x32_bf16 v[110:113], v[148:151], v[196:199], v[110:113]
	v_mfma_f32_16x16x32_bf16 v[106:109], v[164:167], v[196:199], v[106:109]
	v_mfma_f32_16x16x32_bf16 v[94:97], v[148:151], v[204:207], v[94:97]
	v_mfma_f32_16x16x32_bf16 v[90:93], v[164:167], v[204:207], v[90:93]
	v_mfma_f32_16x16x32_bf16 v[78:81], v[148:151], v[232:235], v[78:81]
	v_mfma_f32_16x16x32_bf16 v[74:77], v[164:167], v[232:235], v[74:77]
	v_mfma_f32_16x16x32_bf16 v[118:121], v[168:171], v[184:187], v[118:121]
	v_mfma_f32_16x16x32_bf16 v[114:117], v[176:179], v[184:187], v[114:117]
	v_mfma_f32_16x16x32_bf16 v[102:105], v[168:171], v[192:195], v[102:105]
	v_mfma_f32_16x16x32_bf16 v[98:101], v[176:179], v[192:195], v[98:101]
	v_mfma_f32_16x16x32_bf16 v[86:89], v[168:171], v[200:203], v[86:89]
	v_mfma_f32_16x16x32_bf16 v[82:85], v[176:179], v[200:203], v[82:85]
	v_mfma_f32_16x16x32_bf16 v[70:73], v[168:171], v[228:231], v[70:73]
	v_mfma_f32_16x16x32_bf16 v[66:69], v[176:179], v[228:231], v[66:69]
	v_mfma_f32_16x16x32_bf16 v[118:121], v[172:175], v[188:191], v[118:121]
	v_mfma_f32_16x16x32_bf16 v[114:117], v[180:183], v[188:191], v[114:117]
	v_mfma_f32_16x16x32_bf16 v[102:105], v[172:175], v[196:199], v[102:105]
	v_mfma_f32_16x16x32_bf16 v[98:101], v[180:183], v[196:199], v[98:101]
	v_mfma_f32_16x16x32_bf16 v[86:89], v[172:175], v[204:207], v[86:89]
	v_mfma_f32_16x16x32_bf16 v[82:85], v[180:183], v[204:207], v[82:85]
	v_mfma_f32_16x16x32_bf16 v[70:73], v[172:175], v[232:235], v[70:73]
	v_mfma_f32_16x16x32_bf16 v[66:69], v[180:183], v[232:235], v[66:69]
	s_barrier
	s_add_i32 s41, s41, s48
	v_lshl_add_u64 v[142:143], s[12:13], 0, v[130:131]
	s_mov_b32 m0, s41
	ds_read_b128 v[184:187], v146 offset:16384
	ds_read_b128 v[188:191], v146 offset:17408
	ds_read_b128 v[192:195], v146 offset:18432
	ds_read_b128 v[196:199], v146 offset:19456
	ds_read_b128 v[200:203], v146 offset:20480
	ds_read_b128 v[204:207], v146 offset:21504
	ds_read_b128 v[228:231], v146 offset:22528
	ds_read_b128 v[232:235], v146 offset:23552
	global_load_lds_dwordx4 v[142:143], off
	s_add_i32 m0, s41, 0x2000
	s_add_u32 s62, s12, 0x40000
	v_lshl_add_u64 v[152:153], s[12:13], 0, v[132:133]
	s_addc_u32 s63, s13, 0
	s_add_i32 s41, s60, s48
	global_load_lds_dwordx4 v[152:153], off
	v_lshl_add_u64 v[236:237], s[62:63], 0, v[130:131]
	s_mov_b32 m0, s41
	v_lshl_add_u64 v[238:239], s[36:37], 0, v[132:133]
	global_load_lds_dwordx4 v[236:237], off
	v_lshl_add_u64 v[236:237], s[62:63], 0, v[132:133]
	s_add_i32 m0, s41, 0x2000
	s_nop 0
	global_load_lds_dwordx4 v[236:237], off
	v_lshl_add_u64 v[236:237], s[36:37], 0, v[130:131]
	s_mov_b32 m0, s49
	s_nop 0
	global_load_lds_dwordx4 v[236:237], off
	s_mov_b32 m0, s50
	s_nop 0
	global_load_lds_dwordx4 v[238:239], off
	s_waitcnt vmcnt(8)
	s_waitcnt lgkmcnt(0)
	s_barrier
	s_waitcnt lgkmcnt(0)
	v_mfma_f32_16x16x32_bf16 v[62:65], v[138:141], v[184:187], v[62:65]
	v_mfma_f32_16x16x32_bf16 v[58:61], v[160:163], v[184:187], v[58:61]
	v_mfma_f32_16x16x32_bf16 v[46:49], v[138:141], v[192:195], v[46:49]
	v_mfma_f32_16x16x32_bf16 v[42:45], v[160:163], v[192:195], v[42:45]
	v_mfma_f32_16x16x32_bf16 v[30:33], v[138:141], v[200:203], v[30:33]
	v_mfma_f32_16x16x32_bf16 v[26:29], v[160:163], v[200:203], v[26:29]
	v_mfma_f32_16x16x32_bf16 v[14:17], v[138:141], v[228:231], v[14:17]
	v_mfma_f32_16x16x32_bf16 v[10:13], v[160:163], v[228:231], v[10:13]
	v_mfma_f32_16x16x32_bf16 v[62:65], v[148:151], v[188:191], v[62:65]
	v_mfma_f32_16x16x32_bf16 v[58:61], v[164:167], v[188:191], v[58:61]
	v_mfma_f32_16x16x32_bf16 v[46:49], v[148:151], v[196:199], v[46:49]
	v_mfma_f32_16x16x32_bf16 v[42:45], v[164:167], v[196:199], v[42:45]
	v_mfma_f32_16x16x32_bf16 v[30:33], v[148:151], v[204:207], v[30:33]
	v_mfma_f32_16x16x32_bf16 v[26:29], v[164:167], v[204:207], v[26:29]
	v_mfma_f32_16x16x32_bf16 v[14:17], v[148:151], v[232:235], v[14:17]
	v_mfma_f32_16x16x32_bf16 v[10:13], v[164:167], v[232:235], v[10:13]
	v_mfma_f32_16x16x32_bf16 v[54:57], v[168:171], v[184:187], v[54:57]
	v_mfma_f32_16x16x32_bf16 v[50:53], v[176:179], v[184:187], v[50:53]
	v_mfma_f32_16x16x32_bf16 v[38:41], v[168:171], v[192:195], v[38:41]
	v_mfma_f32_16x16x32_bf16 v[34:37], v[176:179], v[192:195], v[34:37]
	v_mfma_f32_16x16x32_bf16 v[22:25], v[168:171], v[200:203], v[22:25]
	v_mfma_f32_16x16x32_bf16 v[18:21], v[176:179], v[200:203], v[18:21]
	v_mfma_f32_16x16x32_bf16 v[6:9], v[168:171], v[228:231], v[6:9]
	v_mfma_f32_16x16x32_bf16 v[2:5], v[176:179], v[228:231], v[2:5]
	v_mfma_f32_16x16x32_bf16 v[54:57], v[172:175], v[188:191], v[54:57]
	v_mfma_f32_16x16x32_bf16 v[50:53], v[180:183], v[188:191], v[50:53]
	v_mfma_f32_16x16x32_bf16 v[38:41], v[172:175], v[196:199], v[38:41]
	v_mfma_f32_16x16x32_bf16 v[34:37], v[180:183], v[196:199], v[34:37]
	v_mfma_f32_16x16x32_bf16 v[22:25], v[172:175], v[204:207], v[22:25]
	v_mfma_f32_16x16x32_bf16 v[18:21], v[180:183], v[204:207], v[18:21]
	v_mfma_f32_16x16x32_bf16 v[6:9], v[172:175], v[232:235], v[6:9]
	v_mfma_f32_16x16x32_bf16 v[2:5], v[180:183], v[232:235], v[2:5]
	s_barrier
	s_add_i32 s41, 0, 0x18000
	v_add_u32_e32 v147, s41, v144
	s_add_i32 s60, 0, 0x1c000
	ds_read_b128 v[138:141], v147
	ds_read_b128 v[148:151], v147 offset:1024
	ds_read_b128 v[160:163], v147 offset:2048
	ds_read_b128 v[164:167], v147 offset:3072
	v_add_u32_e32 v147, s60, v144
	ds_read_b128 v[168:171], v147
	ds_read_b128 v[172:175], v147 offset:1024
	ds_read_b128 v[176:179], v147 offset:2048
	ds_read_b128 v[180:183], v147 offset:3072
	s_add_u32 s36, s36, 0x40000
	s_addc_u32 s37, s37, 0
	s_mov_b32 m0, s51
	v_lshl_add_u64 v[240:241], s[36:37], 0, v[130:131]
	ds_read_b128 v[184:187], v146 offset:32768
	ds_read_b128 v[188:191], v146 offset:33792
	ds_read_b128 v[192:195], v146 offset:34816
	ds_read_b128 v[196:199], v146 offset:35840
	ds_read_b128 v[200:203], v146 offset:36864
	ds_read_b128 v[204:207], v146 offset:37888
	ds_read_b128 v[228:231], v146 offset:38912
	ds_read_b128 v[232:235], v146 offset:39936
	global_load_lds_dwordx4 v[240:241], off
	v_lshl_add_u64 v[240:241], s[36:37], 0, v[132:133]
	s_mov_b32 m0, s52
	s_nop 0
	global_load_lds_dwordx4 v[240:241], off
	s_waitcnt vmcnt(8)
	s_waitcnt lgkmcnt(0)
	s_barrier
	s_waitcnt lgkmcnt(0)
	v_mfma_f32_16x16x32_bf16 v[126:129], v[138:141], v[184:187], v[126:129]
	v_mfma_f32_16x16x32_bf16 v[122:125], v[160:163], v[184:187], v[122:125]
	v_mfma_f32_16x16x32_bf16 v[110:113], v[138:141], v[192:195], v[110:113]
	v_mfma_f32_16x16x32_bf16 v[106:109], v[160:163], v[192:195], v[106:109]
	v_mfma_f32_16x16x32_bf16 v[94:97], v[138:141], v[200:203], v[94:97]
	v_mfma_f32_16x16x32_bf16 v[90:93], v[160:163], v[200:203], v[90:93]
	v_mfma_f32_16x16x32_bf16 v[78:81], v[138:141], v[228:231], v[78:81]
	v_mfma_f32_16x16x32_bf16 v[74:77], v[160:163], v[228:231], v[74:77]
	v_mfma_f32_16x16x32_bf16 v[126:129], v[148:151], v[188:191], v[126:129]
	v_mfma_f32_16x16x32_bf16 v[122:125], v[164:167], v[188:191], v[122:125]
	v_mfma_f32_16x16x32_bf16 v[110:113], v[148:151], v[196:199], v[110:113]
	v_mfma_f32_16x16x32_bf16 v[106:109], v[164:167], v[196:199], v[106:109]
	v_mfma_f32_16x16x32_bf16 v[94:97], v[148:151], v[204:207], v[94:97]
	v_mfma_f32_16x16x32_bf16 v[90:93], v[164:167], v[204:207], v[90:93]
	v_mfma_f32_16x16x32_bf16 v[78:81], v[148:151], v[232:235], v[78:81]
	v_mfma_f32_16x16x32_bf16 v[74:77], v[164:167], v[232:235], v[74:77]
	v_mfma_f32_16x16x32_bf16 v[118:121], v[168:171], v[184:187], v[118:121]
	v_mfma_f32_16x16x32_bf16 v[114:117], v[176:179], v[184:187], v[114:117]
	v_mfma_f32_16x16x32_bf16 v[102:105], v[168:171], v[192:195], v[102:105]
	v_mfma_f32_16x16x32_bf16 v[98:101], v[176:179], v[192:195], v[98:101]
	v_mfma_f32_16x16x32_bf16 v[86:89], v[168:171], v[200:203], v[86:89]
	v_mfma_f32_16x16x32_bf16 v[82:85], v[176:179], v[200:203], v[82:85]
	v_mfma_f32_16x16x32_bf16 v[70:73], v[168:171], v[228:231], v[70:73]
	v_mfma_f32_16x16x32_bf16 v[66:69], v[176:179], v[228:231], v[66:69]
	v_mfma_f32_16x16x32_bf16 v[118:121], v[172:175], v[188:191], v[118:121]
	v_mfma_f32_16x16x32_bf16 v[114:117], v[180:183], v[188:191], v[114:117]
	v_mfma_f32_16x16x32_bf16 v[102:105], v[172:175], v[196:199], v[102:105]
	v_mfma_f32_16x16x32_bf16 v[98:101], v[180:183], v[196:199], v[98:101]
	v_mfma_f32_16x16x32_bf16 v[86:89], v[172:175], v[204:207], v[86:89]
	v_mfma_f32_16x16x32_bf16 v[82:85], v[180:183], v[204:207], v[82:85]
	v_mfma_f32_16x16x32_bf16 v[70:73], v[172:175], v[232:235], v[70:73]
	v_mfma_f32_16x16x32_bf16 v[66:69], v[180:183], v[232:235], v[66:69]
	s_barrier
	s_add_i32 s36, s41, s48
	v_lshl_add_u64 v[142:143], v[142:143], 0, s[76:77]
	s_mov_b32 m0, s36
	ds_read_b128 v[184:187], v146 offset:49152
	ds_read_b128 v[188:191], v146 offset:50176
	ds_read_b128 v[192:195], v146 offset:51200
	ds_read_b128 v[196:199], v146 offset:52224
	ds_read_b128 v[200:203], v146 offset:53248
	ds_read_b128 v[204:207], v146 offset:54272
	ds_read_b128 v[228:231], v146 offset:55296
	ds_read_b128 v[232:235], v146 offset:56320
	global_load_lds_dwordx4 v[142:143], off
	s_add_i32 m0, s36, 0x2000
	s_add_u32 s12, s12, 0x40080
	v_lshl_add_u64 v[142:143], v[152:153], 0, s[76:77]
	s_addc_u32 s13, s13, 0
	s_add_i32 s36, s60, s48
	global_load_lds_dwordx4 v[142:143], off
	v_lshl_add_u64 v[142:143], s[12:13], 0, v[130:131]
	s_mov_b32 m0, s36
	s_nop 0
	global_load_lds_dwordx4 v[142:143], off
	v_lshl_add_u64 v[142:143], s[12:13], 0, v[132:133]
	s_add_i32 m0, s36, 0x2000
	s_nop 0
	global_load_lds_dwordx4 v[142:143], off
	v_lshl_add_u64 v[142:143], v[236:237], 0, s[76:77]
	s_mov_b32 m0, s55
	s_nop 0
	global_load_lds_dwordx4 v[142:143], off
	v_lshl_add_u64 v[142:143], v[238:239], 0, s[76:77]
	s_mov_b32 m0, s56
	s_nop 0
	global_load_lds_dwordx4 v[142:143], off
	s_waitcnt vmcnt(8)
	s_waitcnt lgkmcnt(0)
	s_barrier
	s_waitcnt lgkmcnt(0)
	v_mfma_f32_16x16x32_bf16 v[62:65], v[138:141], v[184:187], v[62:65]
	v_mfma_f32_16x16x32_bf16 v[58:61], v[160:163], v[184:187], v[58:61]
	v_mfma_f32_16x16x32_bf16 v[46:49], v[138:141], v[192:195], v[46:49]
	v_mfma_f32_16x16x32_bf16 v[42:45], v[160:163], v[192:195], v[42:45]
	v_mfma_f32_16x16x32_bf16 v[30:33], v[138:141], v[200:203], v[30:33]
	v_mfma_f32_16x16x32_bf16 v[26:29], v[160:163], v[200:203], v[26:29]
	v_mfma_f32_16x16x32_bf16 v[14:17], v[138:141], v[228:231], v[14:17]
	v_mfma_f32_16x16x32_bf16 v[10:13], v[160:163], v[228:231], v[10:13]
	v_mfma_f32_16x16x32_bf16 v[62:65], v[148:151], v[188:191], v[62:65]
	v_mfma_f32_16x16x32_bf16 v[58:61], v[164:167], v[188:191], v[58:61]
	v_mfma_f32_16x16x32_bf16 v[46:49], v[148:151], v[196:199], v[46:49]
	v_mfma_f32_16x16x32_bf16 v[42:45], v[164:167], v[196:199], v[42:45]
	v_mfma_f32_16x16x32_bf16 v[30:33], v[148:151], v[204:207], v[30:33]
	v_mfma_f32_16x16x32_bf16 v[26:29], v[164:167], v[204:207], v[26:29]
	v_mfma_f32_16x16x32_bf16 v[14:17], v[148:151], v[232:235], v[14:17]
	v_mfma_f32_16x16x32_bf16 v[10:13], v[164:167], v[232:235], v[10:13]
	v_mfma_f32_16x16x32_bf16 v[54:57], v[168:171], v[184:187], v[54:57]
	v_mfma_f32_16x16x32_bf16 v[50:53], v[176:179], v[184:187], v[50:53]
	v_mfma_f32_16x16x32_bf16 v[38:41], v[168:171], v[192:195], v[38:41]
	v_mfma_f32_16x16x32_bf16 v[34:37], v[176:179], v[192:195], v[34:37]
	v_mfma_f32_16x16x32_bf16 v[22:25], v[168:171], v[200:203], v[22:25]
	v_mfma_f32_16x16x32_bf16 v[18:21], v[176:179], v[200:203], v[18:21]
	v_mfma_f32_16x16x32_bf16 v[6:9], v[168:171], v[228:231], v[6:9]
	v_mfma_f32_16x16x32_bf16 v[2:5], v[176:179], v[228:231], v[2:5]
	v_mfma_f32_16x16x32_bf16 v[54:57], v[172:175], v[188:191], v[54:57]
	v_mfma_f32_16x16x32_bf16 v[50:53], v[180:183], v[188:191], v[50:53]
	v_mfma_f32_16x16x32_bf16 v[38:41], v[172:175], v[196:199], v[38:41]
	v_mfma_f32_16x16x32_bf16 v[34:37], v[180:183], v[196:199], v[34:37]
	v_mfma_f32_16x16x32_bf16 v[22:25], v[172:175], v[204:207], v[22:25]
	v_mfma_f32_16x16x32_bf16 v[18:21], v[180:183], v[204:207], v[18:21]
	v_mfma_f32_16x16x32_bf16 v[6:9], v[172:175], v[232:235], v[6:9]
	v_mfma_f32_16x16x32_bf16 v[2:5], v[180:183], v[232:235], v[2:5]
	s_barrier
	s_add_i32 s40, s40, 2
	s_add_u32 s10, s10, 0x100
	s_addc_u32 s11, s11, 0
	s_add_u32 s38, s38, 0x100
	s_addc_u32 s39, s39, 0
	s_cmp_gt_u32 s40, 13
	s_cbranch_scc0 .LBB0_584
	s_and_b64 vcc, exec, s[22:23]
	s_cbranch_vccz .LBB0_587
	s_barrier
